# proj tail overlap: proj main pass capped at 5888 units, 46 sample-tile units on CUs 0-45 overlapped with the attention queue start; gbar1 split arrive/wait; sample attention items wait on a dependency
# speedup vs baseline: 1.0929x; 1.0031x over previous
; #define PG8_STAGE(bufoff, gbase, voff) do { _Pragma("unroll") for (int _i = 0; _i < 2; ++_i) \
;         __builtin_amdgcn_global_load_lds((const unsigned*)((const char*)(gbase) + (voff)[_i]), (PG8_LAS unsigned*)(lds + (bufoff) + ldsw + _i * 8192), 16, 0, 0); } while (0)
; #define PG8_WAIT_V(n) asm volatile("s_waitcnt vmcnt(" #n ")" ::: "memory")
; #define PG8_BAR __builtin_amdgcn_s_barrier()
;     DI bool next(int i, Unit& u) const {
;     ...
;         int wgid = (int)L; { const int q = nwg / NXCD, r = nwg % NXCD, xcd = wgid % NXCD, off = wgid / NXCD; wgid = (xcd < r ? xcd * (q + 1) : r * (q + 1) + (xcd - r) * q) + off; }
;         const int nig = WGM * nN, gid = wgid / nig, fm = gid * WGM, gsz = (nM - fm) < WGM ? (nM - fm) : WGM;
;         u.pm = fm + ((wgid % nig) % gsz); u.pn = (wgid % nig) / gsz; return true;
; template <class Epi, class Sched>
; __device__ __forceinline__ void gemm_phase(PG8_LAS unsigned char* lds, const Gemm g, const Sched& S, const Epi& E) {
;     ...
;     const char* cA = (const char*)g.A + (size_t)cur.pm * tstep; const char* cB = (const char*)g.Bt + (size_t)cur.pn * tstep;
;     S.a_ready(cur);
;     PG8_STAGE(PG8_SB(0, 0), cB, voffB); PG8_STAGE(PG8_SA(0, 0), cA, voffA); PG8_STAGE(PG8_SB(0, 1), cB + hstep, voffB); PG8_STAGE(PG8_SA(0, 1), cA + hstep, voffA);
;     if (wr == 1) PG8_BAR;
;     PG8_WAIT_V(4); PG8_BAR;
;     PG8_STAGE(PG8_SB(1, 0), cB + kstep, voffB); PG8_STAGE(PG8_SA(1, 0), cA + kstep, voffA); PG8_STAGE(PG8_SB(1, 1), cB + hstep + kstep, voffB);
;     PG8_WAIT_V(6); PG8_BAR;
.LBB0_112:
	s_or_b64 exec, exec, s[0:1]
	s_mov_b32 s34, 0
	v_writelane_b32 v255, s34, 63
	v_readlane_b32 s34, v249, 6
	v_readlane_b32 s35, v249, 7
.Ltr_p_reenter:
	s_waitcnt lgkmcnt(0)
	s_barrier
	v_mov_b32_e32 v8, v153
	s_cmpk_lt_i32 s35, 0x172e
	s_cselect_b64 s[0:1], -1, 0
	s_cmpk_gt_i32 s35, 0x172d
	v_readfirstlane_b32 s36, v8
	s_cbranch_scc1 .LBB0_118
	s_cmpk_lt_u32 s35, 0x1700
	s_cbranch_scc0 .Ltr_p_left
	s_and_b32 s2, s35, 7
	s_lshr_b32 s3, s35, 3
	s_lshl_b32 s2, s2, 2
	s_mov_b32 s4, 0
	s_cmpk_ge_u32 s3, 0xb8
	s_addc_u32 s4, s4, 0
	s_cmpk_ge_u32 s3, 0x170
	s_addc_u32 s4, s4, 0
	s_cmpk_ge_u32 s3, 0x228
	s_addc_u32 s4, s4, 0
	s_add_u32 s2, s2, s4
	s_mul_i32 s4, s4, 0xb8
	s_sub_u32 s3, s3, s4
	s_lshl_b32 s2, s2, 3
	s_and_b32 s4, s3, 7
	s_or_b32 s10, s2, s4
	s_lshr_b32 s8, s3, 3
	s_branch .Ltr_p_join
.Ltr_p_left:
	s_sub_u32 s2, s35, 0x1700
	s_and_b32 s3, s2, 1
	s_add_u32 s10, s3, 0x100
	s_lshr_b32 s8, s2, 1
.Ltr_p_join:
.LBB0_118:
	s_andn2_b64 vcc, exec, s[0:1]
	s_cbranch_vccnz .LBB0_1717
	v_ashrrev_i32_e32 v1, 31, v8
	v_lshrrev_b32_e32 v1, 26, v1
	v_add_u32_e32 v1, v8, v1
	v_ashrrev_i32_e32 v9, 6, v1
	v_bfe_i32 v1, v8, 27, 1
	v_lshlrev_b32_e32 v0, 4, v8
	v_lshrrev_b32_e32 v1, 22, v1
	v_add_u32_e32 v1, v0, v1
	v_and_b32_e32 v1, 0xfffffc00, v1
	v_sub_u32_e32 v1, v0, v1
	v_lshrrev_b32_e32 v2, 4, v1
	v_bitop3_b32 v2, v2, v1, 32 bitop3:0x6c
	v_ashrrev_i32_e32 v1, 31, v1
	v_lshrrev_b32_e32 v1, 26, v1
	v_add_u32_e32 v1, v2, v1
	v_ashrrev_i32_e32 v10, 6, v1
	v_lshlrev_b32_e32 v3, 3, v9
	v_mul_i32_i24_e32 v4, 64, v10
	v_and_b32_e32 v3, -16, v3
	v_sub_u32_e32 v2, v2, v4
	v_add_u32_e32 v1, v10, v3
	v_lshlrev_b32_e32 v3, 5, v9
	v_ashrrev_i16_sdwa v2, v182, sext(v2) dst_sel:DWORD dst_unused:UNUSED_PAD src0_sel:DWORD src1_sel:BYTE_0
	v_and_b32_e32 v3, 32, v3
	v_bfe_i32 v11, v2, 0, 16
	v_and_b32_e32 v5, 3, v10
	s_mov_b32 s1, 0x1fffe0
	v_add_lshl_u32 v3, v3, v11, 1
	v_add_u32_e32 v0, 0x2000, v0
	v_lshlrev_b32_e32 v2, 1, v1
	v_lshrrev_b32_e32 v4, 2, v1
	v_and_or_b32 v5, v1, s1, v5
	v_lshl_add_u32 v18, v1, 11, v3
	v_ashrrev_i32_e32 v1, 31, v0
	v_lshrrev_b32_e32 v1, 22, v1
	v_add_u32_e32 v1, v0, v1
	v_ashrrev_i32_e32 v12, 10, v1
	v_mul_i32_i24_e32 v1, 0x400, v12
	v_sub_u32_e32 v0, v0, v1
	v_and_b32_e32 v2, 24, v2
	v_and_b32_e32 v4, 4, v4
	v_lshrrev_b32_e32 v1, 4, v0
	v_or3_b32 v2, v5, v4, v2
	v_bitop3_b32 v0, v1, v0, 32 bitop3:0x6c
	v_lshl_add_u32 v138, v2, 11, v3
	v_ashrrev_i32_e32 v2, 31, v0
	v_lshrrev_b32_e32 v2, 26, v2
	v_lshlrev_b32_e32 v1, 3, v12
	v_add_u32_e32 v2, v0, v2
	v_and_b32_e32 v1, -16, v1
	v_ashrrev_i32_e32 v13, 6, v2
	s_ashr_i32 s0, s36, 6
	v_add_u32_e32 v1, v13, v1
	v_and_b32_e32 v2, 0xc0, v2
	v_and_b32_e32 v4, 3, v13
	s_ashr_i32 s11, s10, 31
	s_ashr_i32 s9, s8, 31
	v_sub_u32_e32 v0, v0, v2
	v_and_or_b32 v4, v1, s1, v4
	s_ashr_i32 s1, s36, 8
	s_lshl_b32 s37, s0, 10
	s_lshl_b64 s[2:3], s[10:11], 19
	s_lshl_b64 s[4:5], s[8:9], 19
	v_readlane_b32 s6, v249, 46
	v_ashrrev_i16_sdwa v0, v182, sext(v0) dst_sel:DWORD dst_unused:UNUSED_PAD src0_sel:DWORD src1_sel:BYTE_0
	s_add_u32 s14, s6, s4
	v_readlane_b32 s4, v249, 47
	v_lshlrev_b32_e32 v3, 5, v12
	v_bfe_i32 v14, v0, 0, 16
	v_lshlrev_b32_e32 v0, 1, v1
	v_lshrrev_b32_e32 v2, 2, v1
	s_addc_u32 s15, s4, s5
	s_add_i32 s38, s37, 0
	v_and_b32_e32 v3, 32, v3
	v_and_b32_e32 v0, 24, v0
	v_and_b32_e32 v2, 4, v2
	s_add_i32 m0, s38, 0x10000
	v_or3_b32 v0, v4, v2, v0
	v_add_lshl_u32 v2, v3, v14, 1
	global_load_lds_dwordx4 v138, s[14:15]
	s_add_i32 m0, s38, 0x12000
	v_readlane_b32 s4, v249, 0
	v_lshl_add_u32 v142, v0, 11, v2
	v_readlane_b32 s5, v249, 1
	s_add_u32 s16, s4, s2
	global_load_lds_dwordx4 v142, s[14:15]
	s_addc_u32 s17, s5, s3
	s_mov_b32 m0, s38
	s_add_i32 s39, s38, 0x2000
	v_lshl_add_u32 v140, v1, 11, v2
	global_load_lds_dwordx4 v18, s[16:17]
	s_mov_b32 m0, s39
	s_add_u32 s2, s14, 0x40000
	global_load_lds_dwordx4 v140, s[16:17]
	s_addc_u32 s3, s15, 0
	s_add_i32 m0, s38, 0x14000
	v_mov_b32_e32 v139, v17
	global_load_lds_dwordx4 v138, s[2:3]
	s_add_i32 m0, s38, 0x16000
	v_mov_b32_e32 v143, v17
	global_load_lds_dwordx4 v142, s[2:3]
	s_add_u32 s2, s16, 0x40000
	s_addc_u32 s3, s17, 0
	s_add_i32 s40, s38, 0x4000
	s_mov_b32 m0, s40
	s_add_i32 s41, s38, 0x6000
	global_load_lds_dwordx4 v18, s[2:3]
	s_mov_b32 m0, s41
	v_mov_b32_e32 v19, v17
	global_load_lds_dwordx4 v140, s[2:3]
	v_mov_b32_e32 v141, v17
	v_lshl_add_u64 v[6:7], s[14:15], 0, v[138:139]
	v_lshl_add_u64 v[4:5], s[14:15], 0, v[142:143]
	v_lshl_add_u64 v[2:3], s[16:17], 0, v[18:19]
	s_cmp_lg_u32 s1, 1
	v_lshl_add_u64 v[0:1], s[16:17], 0, v[140:141]
	s_cbranch_scc1 .LBB0_121
	s_barrier

;     DI bool next(int i, Unit& u) const {
;         const long L = (long)i * G + c; if (L >= nwg) return false;
;         int wgid = (int)L; { const int q = nwg / NXCD, r = nwg % NXCD, xcd = wgid % NXCD, off = wgid / NXCD; wgid = (xcd < r ? xcd * (q + 1) : r * (q + 1) + (xcd - r) * q) + off; }
;         const int nig = WGM * nN, gid = wgid / nig, fm = gid * WGM, gsz = (nM - fm) < WGM ? (nM - fm) : WGM;
;         u.pm = fm + ((wgid % nig) % gsz); u.pn = (wgid % nig) / gsz; return true;
; template <class Epi, class Sched>
; __device__ __forceinline__ void gemm_phase(PG8_LAS unsigned char* lds, const Gemm g, const Sched& S, const Epi& E) {
;     ...
;         const bool has_next = S.next(ui + 1, nxt);
;         const char* nA = has_next ? (const char*)g.A + (size_t)nxt.pm * tstep : cA; const char* nB = has_next ? (const char*)g.Bt + (size_t)nxt.pn * tstep : cB;
;         for (int t = 0; t < nt; t += 2) {
;             const bool last = (t == nt - 2);
;             const char* a1 = cA + (size_t)(t + 1) * kstep;
;             const char* a2 = last ? nA : cA + (size_t)(t + 2) * kstep; const char* b2 = last ? nB : cB + (size_t)(t + 2) * kstep;
;             const char* a3 = a2 + kstep; const char* b3 = b2 + kstep;
;             if (last && has_next) S.a_ready(nxt);
;             if constexpr (Epi::MIDK) { if (t == nt / 2) E.mid(acc, cur, wr, wc, fr, fq); }
;             PG8_LDB(B0, 0, 0); PG8_SCHED; PG8_LDA(At, 0, 0); PG8_STAGE(PG8_SA(1, 1), a1 + hstep, voffA);
;             PG8_WAIT_L(8); PG8_BAR; PG8_WAIT_L(0); PG8_MMA(0, 0, At, B0); PG8_BAR; PG8_SCHED;
;             PG8_LDB(B1, 0, 1); PG8_STAGE(PG8_SB(0, 0), b2, voffB);
;             PG8_BAR; PG8_WAIT_L(0); PG8_MMA(0, 1, At, B1); PG8_BAR;
;             PG8_LDA(At, 0, 1); PG8_STAGE(PG8_SA(0, 0), a2, voffA);
;             PG8_BAR; PG8_WAIT_L(0); PG8_MMA(1, 0, At, B0); PG8_BAR; PG8_SCHED;
;             PG8_STAGE(PG8_SB(0, 1), b2 + hstep, voffB);
;             PG8_WAIT_V(6); PG8_BAR; PG8_MMA(1, 1, At, B1); PG8_BAR;
;             PG8_LDB(B0, 1, 0); PG8_SCHED; PG8_LDA(At, 1, 0); PG8_STAGE(PG8_SA(0, 1), a2 + hstep, voffA);
;             PG8_WAIT_L(8); PG8_BAR; PG8_WAIT_L(0); PG8_MMA(0, 0, At, B0); PG8_BAR; PG8_SCHED;
;             PG8_LDB(B1, 1, 1); PG8_STAGE(PG8_SB(1, 0), b3, voffB);
;             PG8_BAR; PG8_WAIT_L(0); PG8_MMA(0, 1, At, B1); PG8_BAR;
;             PG8_LDA(At, 1, 1); PG8_STAGE(PG8_SA(1, 0), a3, voffA);
.LBB0_123:
	s_add_i32 s47, s47, 1
	s_mul_i32 s0, s47, s45
	s_mul_hi_u32 s1, s47, s34
	s_add_i32 s1, s1, s0
	s_mul_i32 s0, s47, s34
	s_add_u32 s6, s0, s35
	s_addc_u32 s7, s1, s46
	v_mov_b64_e32 v[0:1], 0x16ff
	v_cmp_gt_i64_e64 s[0:1], s[6:7], v[0:1]
	s_mov_b64 s[2:3], s[16:17]
	s_mov_b64 s[4:5], s[14:15]
	s_mov_b32 s48, s10
	s_mov_b32 s23, s8
	s_and_b64 vcc, exec, s[0:1]
	s_cbranch_vccnz .LBB0_129
	s_and_b32 s9, s6, 7
	s_lshr_b32 s11, s6, 3
	s_lshl_b32 s9, s9, 2
	s_mov_b32 s14, 0
	s_cmpk_ge_u32 s11, 0xb8
	s_addc_u32 s14, s14, 0
	s_cmpk_ge_u32 s11, 0x170
	s_addc_u32 s14, s14, 0
	s_cmpk_ge_u32 s11, 0x228
	s_addc_u32 s14, s14, 0
	s_add_u32 s9, s9, s14
	s_mul_i32 s14, s14, 0xb8
	s_sub_u32 s11, s11, s14
	s_lshl_b32 s9, s9, 3
	s_and_b32 s14, s11, 7
	s_or_b32 s10, s9, s14
	s_lshr_b32 s8, s11, 3
.LBB0_129:
	v_mov_b64_e32 v[0:1], 0x1700
	s_ashr_i32 s11, s10, 31
	v_cmp_lt_i64_e32 vcc, s[6:7], v[0:1]
	s_lshl_b64 s[6:7], s[10:11], 19
	v_readlane_b32 s14, v249, 0
	v_readlane_b32 s15, v249, 1
	s_add_u32 s16, s14, s6
	s_addc_u32 s17, s15, s7
	s_and_b64 s[6:7], vcc, exec
	s_cselect_b32 s11, s17, s3
	s_cselect_b32 s22, s16, s2
	s_ashr_i32 s9, s8, 31
	s_lshl_b64 s[6:7], s[8:9], 19
	v_readlane_b32 s9, v249, 46
	s_add_u32 s14, s9, s6
	v_readlane_b32 s6, v249, 47
	s_addc_u32 s15, s6, s7
	s_and_b64 s[6:7], vcc, exec
	s_cselect_b32 s9, s15, s5
	s_cselect_b32 s24, s14, s4
	s_add_u32 s2, s2, 0x40080
	s_addc_u32 s3, s3, 0
	s_add_u32 s25, s4, 0x100
	v_mov_b32_e32 v0, 0
	s_addc_u32 s26, s5, 0
	s_mov_b32 s27, -2
	v_mov_b32_e32 v1, v0
	v_mov_b32_e32 v2, v0
	v_mov_b32_e32 v3, v0
	v_mov_b32_e32 v4, v0
	v_mov_b32_e32 v5, v0
	v_mov_b32_e32 v6, v0
	v_mov_b32_e32 v7, v0
	s_waitcnt lgkmcnt(0)
	v_mov_b32_e32 v8, v0
	v_mov_b32_e32 v9, v0
	v_mov_b32_e32 v10, v0
	v_mov_b32_e32 v11, v0
	v_mov_b32_e32 v12, v0
	v_mov_b32_e32 v13, v0
	v_mov_b32_e32 v14, v0
	v_mov_b32_e32 v15, v0
	v_mov_b32_e32 v22, v0
	v_mov_b32_e32 v23, v0
	v_mov_b32_e32 v24, v0
	v_mov_b32_e32 v25, v0
	v_mov_b32_e32 v26, v0
	v_mov_b32_e32 v27, v0
	v_mov_b32_e32 v28, v0
	v_mov_b32_e32 v29, v0
	v_mov_b32_e32 v30, v0
	v_mov_b32_e32 v31, v0
	v_mov_b32_e32 v32, v0
	v_mov_b32_e32 v33, v0
	v_mov_b32_e32 v34, v0
	v_mov_b32_e32 v35, v0
	v_mov_b32_e32 v36, v0
	v_mov_b32_e32 v37, v0
	v_mov_b32_e32 v70, v0
	v_mov_b32_e32 v71, v0
	v_mov_b32_e32 v72, v0
	v_mov_b32_e32 v73, v0
	v_mov_b32_e32 v74, v0
	v_mov_b32_e32 v75, v0
	v_mov_b32_e32 v76, v0
	v_mov_b32_e32 v77, v0
	v_mov_b32_e32 v78, v0
	v_mov_b32_e32 v79, v0
	v_mov_b32_e32 v80, v0
	v_mov_b32_e32 v81, v0
	v_mov_b32_e32 v82, v0
	v_mov_b32_e32 v83, v0
	v_mov_b32_e32 v84, v0
	v_mov_b32_e32 v85, v0
	v_mov_b32_e32 v86, v0
	v_mov_b32_e32 v87, v0
	v_mov_b32_e32 v88, v0
	v_mov_b32_e32 v89, v0
	v_mov_b32_e32 v90, v0
	v_mov_b32_e32 v91, v0
	v_mov_b32_e32 v92, v0
	v_mov_b32_e32 v93, v0
	v_mov_b32_e32 v94, v0
	v_mov_b32_e32 v95, v0
	v_mov_b32_e32 v96, v0
	v_mov_b32_e32 v97, v0
	v_mov_b32_e32 v98, v0
	v_mov_b32_e32 v99, v0
	v_mov_b32_e32 v100, v0
	v_mov_b32_e32 v101, v0
	v_mov_b32_e32 v38, v0
	v_mov_b32_e32 v39, v0
	v_mov_b32_e32 v40, v0
	v_mov_b32_e32 v41, v0
	v_mov_b32_e32 v42, v0
	v_mov_b32_e32 v43, v0
	v_mov_b32_e32 v44, v0
	v_mov_b32_e32 v45, v0
	v_mov_b32_e32 v46, v0
	v_mov_b32_e32 v47, v0
	v_mov_b32_e32 v48, v0
	v_mov_b32_e32 v49, v0
	v_mov_b32_e32 v50, v0
	v_mov_b32_e32 v51, v0
	v_mov_b32_e32 v52, v0
	v_mov_b32_e32 v53, v0
	v_mov_b32_e32 v54, v0
	v_mov_b32_e32 v55, v0
	v_mov_b32_e32 v56, v0
	v_mov_b32_e32 v57, v0
	v_mov_b32_e32 v58, v0
	v_mov_b32_e32 v59, v0
	v_mov_b32_e32 v60, v0
	v_mov_b32_e32 v61, v0
	v_mov_b32_e32 v62, v0
	v_mov_b32_e32 v63, v0
	v_mov_b32_e32 v64, v0
	v_mov_b32_e32 v65, v0
	v_mov_b32_e32 v66, v0
	v_mov_b32_e32 v67, v0
	v_mov_b32_e32 v68, v0
	v_mov_b32_e32 v69, v0
	v_mov_b32_e32 v102, v0
	v_mov_b32_e32 v103, v0
	v_mov_b32_e32 v104, v0
	v_mov_b32_e32 v105, v0
	v_mov_b32_e32 v106, v0
	v_mov_b32_e32 v107, v0
	v_mov_b32_e32 v108, v0
	v_mov_b32_e32 v109, v0
	v_mov_b32_e32 v110, v0
	v_mov_b32_e32 v111, v0
	v_mov_b32_e32 v112, v0
	v_mov_b32_e32 v113, v0
	v_mov_b32_e32 v114, v0
	v_mov_b32_e32 v115, v0
	v_mov_b32_e32 v116, v0
	v_mov_b32_e32 v117, v0
	v_mov_b32_e32 v118, v0
	v_mov_b32_e32 v119, v0
	v_mov_b32_e32 v120, v0
	v_mov_b32_e32 v121, v0
	v_mov_b32_e32 v122, v0
	v_mov_b32_e32 v123, v0
	v_mov_b32_e32 v124, v0
	v_mov_b32_e32 v125, v0
	v_mov_b32_e32 v126, v0
	v_mov_b32_e32 v127, v0
	v_mov_b32_e32 v128, v0
	v_mov_b32_e32 v129, v0
	v_mov_b32_e32 v130, v0
	v_mov_b32_e32 v131, v0
	v_mov_b32_e32 v132, v0
	v_mov_b32_e32 v133, v0
	s_mov_b64 s[50:51], 0x80

; DI int otid() { int t = threadIdx.x; asm volatile("" : "+v"(t)); return t; }
; DI void gbar(unsigned* ctr, unsigned target) {
;   asm volatile("s_waitcnt vmcnt(0)" ::: "memory");
;   __syncthreads();
;   if (otid() == 0) {
;     __builtin_amdgcn_fence(__ATOMIC_RELEASE, "agent");
;     asm volatile("s_waitcnt vmcnt(0)" ::: "memory");
;     __hip_atomic_fetch_add(ctr, 1u, __ATOMIC_RELAXED, __HIP_MEMORY_SCOPE_AGENT);
;     while (__hip_atomic_load(ctr, __ATOMIC_RELAXED, __HIP_MEMORY_SCOPE_AGENT) < target) __builtin_amdgcn_s_sleep(2);
;     __builtin_amdgcn_fence(__ATOMIC_ACQUIRE, "agent");
;     asm volatile("s_waitcnt vmcnt(0)" ::: "memory");
;   }
;   __syncthreads();
; }
.LBB0_1717:
	s_waitcnt vmcnt(0) lgkmcnt(0)
	s_barrier
	v_readlane_b32 s6, v255, 63
	v_readlane_b32 s7, v249, 7
	v_cmp_eq_u32_e32 vcc, 0, v153
	s_and_saveexec_b64 s[0:1], vcc
	s_cbranch_execz .Ltr_p_arr
	buffer_wbl2 sc1
	s_waitcnt vmcnt(0)
	v_readlane_b32 s2, v249, 44
	v_readlane_b32 s3, v249, 45
	s_lshl_b32 s4, s6, 3
	s_add_u32 s2, s2, s4
	s_addc_u32 s3, s3, 0
	s_nop 4
	global_atomic_add v17, v182, s[2:3]
.Ltr_p_arr:
	s_or_b64 exec, exec, s[0:1]
	s_cmp_lg_u32 s6, 0
	s_cbranch_scc1 .Ltr_p_wait
	s_cmp_lt_u32 s7, 46
	s_cbranch_scc0 .Ltr_p_wait
	s_mov_b32 s2, 1
	v_writelane_b32 v255, s2, 63
	v_readlane_b32 s34, v249, 6
	s_add_i32 s35, s7, 0x1700
	s_branch .Ltr_p_reenter
.Ltr_p_wait:
	v_cmp_eq_u32_e32 vcc, 0, v153
	s_and_saveexec_b64 s[0:1], vcc
	s_cbranch_execz .LBB0_1723
	v_readlane_b32 s4, v249, 44
	v_readlane_b32 s5, v249, 45
	v_readlane_b32 s2, v251, 4
	s_add_i32 s2, s2, 1
	v_readlane_b32 s3, v249, 6
	s_mul_i32 s2, s2, s3
	s_nop 1
	global_load_dword v0, v17, s[4:5] sc1
	s_waitcnt vmcnt(0)
	v_cmp_le_u32_e32 vcc, s2, v0
	s_cbranch_vccnz .LBB0_1722

; DI void phase_attn(const Params& p, int layer, char* smem) {
;     ...
;   while (item < total) {
;     int nxt = 0;
;     if (tid == 0) nxt = atomicAdd(&(reinterpret_cast<int*>(p.ws + OFF_CTR))[layer], 1);
;     if (item < 16) dsa_item<1>(p, item >> 1, item & 1, smem);
;     else if (item < 2064) { const int i = item - 16; dsa_item<0>(p, i >> 6, 63 - (i & 63), smem); }
;     else if (item < 2096) { const int i = item - 2064; sb_item<1>(p, i >> 2, 2 * (i & 3) + (w >> 2), (w & 3) * 16); }
;     else { const int i = item - 2096; const int tile = 15 - (i >> 8), bh = i & 255; sb_item<0>(p, bh >> 3, bh & 7, tile * 128 + w * 16); }
.LBB0_1746:
	s_or_b64 exec, exec, s[0:1]
	s_cmp_gt_i32 s33, 15
	s_cbranch_scc0 .Ltr_a_wait
	s_add_i32 s0, s33, 0xfffff7f0
	s_cmp_lt_u32 s0, 32
	s_cbranch_scc0 .Ltr_a_nowait
.Ltr_a_wait:
	v_readlane_b32 s4, v249, 44
	v_readlane_b32 s5, v249, 45
	v_readlane_b32 s2, v251, 8
	s_mul_i32 s2, s2, 46
	s_add_i32 s2, s2, 46
	s_nop 2
.Ltr_a_spin:
	global_load_dword v0, v17, s[4:5] offset:8 sc1
	s_waitcnt vmcnt(0)
	v_readfirstlane_b32 s3, v0
	s_cmp_ge_u32 s3, s2
	s_cbranch_scc1 .Ltr_a_spun
	s_sleep 2
	s_branch .Ltr_a_spin

; DI int otid() { int t = threadIdx.x; asm volatile("" : "+v"(t)); return t; }
; template <int grp>
; DI void sb_item(const Params& p, int b, int h, int t0) {
;   const int tid = otid(), w = tid >> 6, lane = tid & 63, c = lane & 15, q4 = lane >> 4;
;   const int T = grp ? LS : SEQ;
;   const int qpos0 = grp ? PAST + t0 : t0;
;   const int m0 = grp ? MP + b * DEC_SEQ + t0 : b * SEQ + t0;
;   const bf16_t* Kb = (grp ? (reinterpret_cast<bf16_t*>(p.ws + OFF_KAS)) : (reinterpret_cast<bf16_t*>(p.ws + OFF_KAP))) + (size_t)b * T * 512 + h * 64;
;   const bf16_t* VTb = (grp ? (reinterpret_cast<bf16_t*>(p.ws + OFF_VATS)) : (reinterpret_cast<bf16_t*>(p.ws + OFF_VATP))) + (size_t)(b * 8 + h) * 64 * T;
;   const bf16_t* qp = (reinterpret_cast<bf16_t*>(p.ws + OFF_QAB)) + (size_t)(m0 + c) * 1024 + h * 64 + q4 * 8;
;   const bf16x8 qf0 = ld8(qp), qf1 = ld8(qp + 32);
;   const int qpos = qpos0 + c;
;   float R = 0.f;
;   f32x4 O[4];
; #pragma unroll
;   for (int dt = 0; dt < 4; ++dt) O[dt] = f32x4{0.f, 0.f, 0.f, 0.f};
;   bf16x8 kfA[2][2], vfA[4], kfB[2][2], vfB[4];
;   auto loadkv = [&](int kb, bf16x8 (&kf)[2][2], bf16x8 (&vf)[4]) {
;     const int s0 = kb * 32;
; #pragma unroll
;     for (int kt = 0; kt < 2; ++kt) { const bf16_t* kp = Kb + (size_t)(s0 + 16 * kt + c) * 512 + q4 * 8; kf[kt][0] = ld8(kp); kf[kt][1] = ld8(kp + 32); }
; #pragma unroll
;     for (int dt = 0; dt < 4; ++dt) {
;       const bf16_t* vp = VTb + (size_t)(16 * dt + c) * T + s0 + 4 * q4;
;       bf16x4 lo = ld4(vp), hi = ld4(vp + 16);
;       vf[dt] = __builtin_shufflevector(lo, hi, 0, 1, 2, 3, 4, 5, 6, 7);
;     }
;   };
; DI void phase_attn(const Params& p, int layer, char* smem) {
;     ...
;     if (item < 16) dsa_item<1>(p, item >> 1, item & 1, smem);
;     else if (item < 2064) { const int i = item - 16; dsa_item<0>(p, i >> 6, 63 - (i & 63), smem); }
;     else if (item < 2096) { const int i = item - 2064; sb_item<1>(p, i >> 2, 2 * (i & 3) + (w >> 2), (w & 3) * 16); }
;     else { const int i = item - 2096; const int tile = 15 - (i >> 8), bh = i & 255; sb_item<0>(p, bh >> 3, bh & 7, tile * 128 + w * 16); }
.Ltr_a_nowait:
	s_cmp_gt_i32 s33, 15
	s_mov_b64 s[0:1], -1
	s_cbranch_scc0 .LBB0_1757
	s_cmpk_gt_u32 s33, 0x80f
	s_cbranch_scc0 .LBB0_1770
	v_readlane_b32 s22, v251, 6
	s_cmpk_gt_u32 s33, 0x82f
	v_readlane_b32 s23, v251, 7
	s_cbranch_scc0 .LBB0_1759
	s_add_i32 s0, s33, 0xfffff7d0
	s_bfe_u32 s2, s0, 0x50003
	s_lshr_b32 s0, s0, 1
	s_and_b32 s0, s0, 0x7fffff80
	v_mov_b32_e32 v60, v153
	v_subrev_u32_e32 v4, s0, v163
	s_movk_i32 s5, 0x780
	v_and_b32_e32 v21, 15, v60
	v_add3_u32 v105, v4, v21, s5
	v_lshl_add_u32 v102, s2, 11, v105
	s_and_b32 s3, s33, 7
	s_lshl_b32 s4, s2, 21
	v_readlane_b32 s0, v250, 22
	v_ashrrev_i32_e32 v103, 31, v102
	v_readlane_b32 s6, v250, 28
	v_readlane_b32 s1, v250, 23
	s_add_u32 s0, s0, s4
	v_lshlrev_b64 v[0:1], 11, v[102:103]
	v_readlane_b32 s7, v250, 29
	s_mov_b32 s9, s23
	v_bfe_u32 v61, v60, 4, 2
	s_addc_u32 s1, s1, 0
	s_lshl_b32 s8, s3, 7
	v_lshl_add_u64 v[0:1], s[6:7], 0, v[0:1]
	v_lshl_add_u64 v[18:19], v[0:1], 0, s[8:9]
	v_lshlrev_b32_e32 v0, 4, v61
	v_mov_b32_e32 v1, v17
	v_lshl_add_u64 v[2:3], v[18:19], 0, v[0:1]
	v_add_u32_e32 v62, 0x78e, v4
	global_load_dwordx4 v[8:11], v[2:3], off
	global_load_dwordx4 v[12:15], v[2:3], off offset:64
	v_and_b32_e32 v2, 0xffffffe0, v62
	v_or_b32_e32 v4, v21, v2
	v_ashrrev_i32_e32 v5, 31, v4
	s_lshl_b32 s22, s3, 6
	v_lshlrev_b64 v[6:7], 10, v[4:5]
	v_or_b32_e32 v4, 16, v4
	s_add_u32 s0, s0, s8
	v_ashrrev_i32_e32 v5, 31, v4
	s_addc_u32 s1, s1, 0
	s_lshl_b32 s2, s3, 18
	v_lshlrev_b64 v[4:5], 10, v[4:5]
	s_or_b32 s2, s2, s4
	v_readlane_b32 s4, v250, 18
	v_lshl_add_u64 v[6:7], s[0:1], 0, v[6:7]
	v_lshl_add_u64 v[4:5], s[0:1], 0, v[4:5]
	v_readlane_b32 s5, v250, 19
	s_add_u32 s2, s4, s2
	v_lshl_add_u64 v[6:7], v[6:7], 0, v[0:1]
	v_lshl_add_u64 v[4:5], v[4:5], 0, v[0:1]
	s_addc_u32 s3, s5, 0
	global_load_dwordx4 v[22:25], v[6:7], off
	global_load_dwordx4 v[26:29], v[6:7], off offset:64
	global_load_dwordx4 v[34:37], v[4:5], off
	global_load_dwordx4 v[38:41], v[4:5], off offset:64
	v_lshlrev_b32_e32 v4, 12, v21
	v_mov_b32_e32 v5, v17
	v_ashrrev_i32_e32 v3, 31, v2
	v_lshl_add_u64 v[4:5], s[2:3], 0, v[4:5]
	s_mov_b64 s[2:3], 0x10000
	v_lshlrev_b64 v[6:7], 1, v[2:3]
	v_lshl_add_u64 v[32:33], v[4:5], 0, s[2:3]
	v_lshlrev_b32_e32 v16, 3, v61
	v_lshl_add_u64 v[30:31], v[4:5], 0, v[6:7]
	v_lshl_add_u64 v[42:43], v[32:33], 0, v[6:7]
	v_lshl_add_u64 v[30:31], v[30:31], 0, v[16:17]
	v_lshl_add_u64 v[48:49], v[42:43], 0, v[16:17]
	s_mov_b64 s[2:3], 0x20000
	global_load_dwordx2 v[42:43], v[30:31], off
	global_load_dwordx2 v[44:45], v[30:31], off offset:32
	global_load_dwordx2 v[46:47], v[48:49], off
	s_nop 0
	global_load_dwordx2 v[48:49], v[48:49], off offset:32
	v_lshl_add_u64 v[30:31], v[4:5], 0, s[2:3]
	s_mov_b64 s[2:3], 0x30000
	v_lshl_add_u64 v[50:51], v[30:31], 0, v[6:7]
	v_lshl_add_u64 v[58:59], v[4:5], 0, s[2:3]
	v_lshl_add_u64 v[52:53], v[50:51], 0, v[16:17]
	v_lshl_add_u64 v[6:7], v[58:59], 0, v[6:7]
	v_lshl_add_u64 v[6:7], v[6:7], 0, v[16:17]
	global_load_dwordx2 v[50:51], v[52:53], off
	s_nop 0
	global_load_dwordx2 v[52:53], v[52:53], off offset:32
	s_nop 0
	global_load_dwordx2 v[54:55], v[6:7], off
	global_load_dwordx2 v[56:57], v[6:7], off offset:32
	v_lshl_add_u64 v[106:107], s[0:1], 0, v[0:1]
	v_and_b32_e32 v0, 16, v60
	v_cmp_eq_u32_e32 vcc, 0, v0
	v_and_b32_e32 v0, 32, v60
	v_mov_b32_e32 v119, 0
	v_ashrrev_i32_e32 v122, 5, v62
	v_lshlrev_b32_e32 v104, 2, v61
	v_lshl_add_u64 v[108:109], v[4:5], 0, v[16:17]
	v_lshl_add_u64 v[110:111], v[32:33], 0, v[16:17]
	v_lshl_add_u64 v[112:113], v[30:31], 0, v[16:17]
	v_lshl_add_u64 v[114:115], v[58:59], 0, v[16:17]
	v_cmp_eq_u32_e64 s[0:1], 0, v0
	v_subrev_u32_e32 v116, 64, v2
	s_mov_b64 s[18:19], 0
	v_mov_b32_e32 v0, v119
	v_mov_b32_e32 v1, v119
	v_mov_b32_e32 v2, v119
	v_mov_b32_e32 v3, v119
	v_mov_b32_e32 v4, v119
	v_mov_b32_e32 v5, v119
	v_mov_b32_e32 v6, v119
	v_mov_b32_e32 v7, v119
	v_mov_b32_e32 v30, v119
	v_mov_b32_e32 v31, v119
	v_mov_b32_e32 v32, v119
	v_mov_b32_e32 v33, v119
	v_mov_b32_e32 v58, v119
	v_mov_b32_e32 v59, v119
	v_mov_b32_e32 v60, v119
	v_mov_b32_e32 v61, v119
	s_branch .LBB0_1752
